# V^T scratch stored in 32-key blocks (writer in prep, reader in attention): half as many cache lines per P.V operand
# speedup vs baseline: 1.0489x; 1.0130x over previous
.LBB0_422:
	s_ashr_i32 s8, s6, 7
	s_ashr_i32 s9, s8, 31
	s_lshl_b64 s[10:11], s[8:9], 11
	s_and_b32 s8, s7, 0x7c0
	s_or_b32 s1, s10, s8
	s_mul_i32 s9, s11, 0x1e00
	s_mul_hi_u32 s10, s1, 0x1e00
	s_ashr_i32 s0, s6, 5
	s_add_i32 s10, s10, s9
	s_mulk_i32 s1, 0x1e00
	s_add_u32 s1, s20, s1
	s_addc_u32 s9, s21, s10
	s_lshl_b32 s10, s0, 7
	s_and_b32 s10, s10, 0x180
	s_add_u32 s10, s1, s10
	s_addc_u32 s11, s9, 0
	v_lshl_add_u64 v[2:3], s[10:11], 0, v[156:157]
	v_add_co_u32_e32 v6, vcc, s72, v2
	global_load_ushort v11, v156, s[10:11] offset:1024
	s_nop 0
	v_addc_co_u32_e32 v7, vcc, 0, v3, vcc
	global_load_ushort v12, v[6:7], off offset:512
	v_add_co_u32_e32 v6, vcc, s86, v2
	s_mov_b32 s1, 0x3e000
	s_nop 0
	v_addc_co_u32_e32 v7, vcc, 0, v3, vcc
	global_load_ushort v13, v[6:7], off
	v_add_co_u32_e32 v6, vcc, s18, v2
	s_lshl_b32 s44, s8, 1
	s_nop 0
	v_addc_co_u32_e32 v7, vcc, 0, v3, vcc
	global_load_ushort v14, v[6:7], off offset:3584
	v_add_co_u32_e32 v6, vcc, s19, v2
	s_add_i32 s6, s6, s38
	s_nop 0
	v_addc_co_u32_e32 v7, vcc, 0, v3, vcc
	global_load_ushort v15, v[6:7], off offset:3072
	v_add_co_u32_e32 v6, vcc, s87, v2
	s_add_i32 s7, s7, s61
	s_nop 0
	v_addc_co_u32_e32 v7, vcc, 0, v3, vcc
	global_load_ushort v16, v[6:7], off offset:2560
	v_add_co_u32_e32 v6, vcc, s17, v2
	s_nop 1
	v_addc_co_u32_e32 v7, vcc, 0, v3, vcc
	global_load_ushort v17, v[6:7], off offset:2048
	v_add_co_u32_e32 v6, vcc, s5, v2
	s_nop 1
	v_addc_co_u32_e32 v7, vcc, 0, v3, vcc
	global_load_ushort v18, v[6:7], off offset:1536
	v_add_co_u32_e32 v6, vcc, s40, v2
	s_nop 1
	v_addc_co_u32_e32 v7, vcc, 0, v3, vcc
	global_load_ushort v19, v[6:7], off offset:1024
	v_add_co_u32_e32 v6, vcc, s62, v2
	s_nop 1
	v_addc_co_u32_e32 v7, vcc, 0, v3, vcc
	global_load_ushort v20, v[6:7], off offset:512
	v_add_co_u32_e32 v6, vcc, s80, v2
	s_nop 1
	v_addc_co_u32_e32 v7, vcc, 0, v3, vcc
	global_load_ushort v21, v[6:7], off
	v_add_co_u32_e32 v6, vcc, s73, v2
	s_nop 1
	v_addc_co_u32_e32 v7, vcc, 0, v3, vcc
	global_load_ushort v22, v[6:7], off offset:3584
	v_add_co_u32_e32 v6, vcc, s41, v2
	s_nop 1
	v_addc_co_u32_e32 v7, vcc, 0, v3, vcc
	global_load_ushort v23, v[6:7], off offset:3072
	v_add_co_u32_e32 v6, vcc, s14, v2
	s_nop 1
	v_addc_co_u32_e32 v7, vcc, 0, v3, vcc
	global_load_ushort v24, v[6:7], off offset:2560
	v_add_co_u32_e32 v6, vcc, s15, v2
	s_nop 1
	v_addc_co_u32_e32 v7, vcc, 0, v3, vcc
	global_load_ushort v25, v[6:7], off offset:2048
	v_add_co_u32_e32 v6, vcc, s16, v2
	s_nop 1
	v_addc_co_u32_e32 v7, vcc, 0, v3, vcc
	global_load_ushort v6, v[6:7], off offset:1536
	s_waitcnt vmcnt(15)
	ds_write_b16 v10, v11
	s_waitcnt vmcnt(14)
	ds_write_b16 v10, v12 offset:132
	s_waitcnt vmcnt(13)
	ds_write_b16 v10, v13 offset:264
	s_waitcnt vmcnt(12)
	ds_write_b16 v10, v14 offset:396
	s_waitcnt vmcnt(11)
	ds_write_b16 v10, v15 offset:528
	s_waitcnt vmcnt(10)
	ds_write_b16 v10, v16 offset:660
	s_waitcnt vmcnt(9)
	ds_write_b16 v10, v17 offset:792
	s_waitcnt vmcnt(8)
	ds_write_b16 v10, v18 offset:924
	s_waitcnt vmcnt(7)
	ds_write_b16 v10, v19 offset:1056
	s_waitcnt vmcnt(6)
	ds_write_b16 v10, v20 offset:1188
	s_waitcnt vmcnt(5)
	ds_write_b16 v10, v21 offset:1320
	s_waitcnt vmcnt(4)
	ds_write_b16 v10, v22 offset:1452
	s_waitcnt vmcnt(3)
	ds_write_b16 v10, v23 offset:1584
	s_waitcnt vmcnt(2)
	ds_write_b16 v10, v24 offset:1716
	s_waitcnt vmcnt(1)
	ds_write_b16 v10, v25 offset:1848
	s_waitcnt vmcnt(0)
	ds_write_b16 v10, v6 offset:1980
	v_add_co_u32_e32 v6, vcc, s76, v2
	s_nop 1
	v_addc_co_u32_e32 v7, vcc, 0, v3, vcc
	global_load_ushort v11, v[6:7], off offset:1024
	v_add_co_u32_e32 v6, vcc, s91, v2
	s_nop 1
	v_addc_co_u32_e32 v7, vcc, 0, v3, vcc
	global_load_ushort v12, v[6:7], off offset:512
	v_add_co_u32_e32 v6, vcc, s63, v2
	s_nop 1
	v_addc_co_u32_e32 v7, vcc, 0, v3, vcc
	global_load_ushort v13, v[6:7], off
	v_add_co_u32_e32 v6, vcc, s31, v2
	s_nop 1
	v_addc_co_u32_e32 v7, vcc, 0, v3, vcc
	global_load_ushort v14, v[6:7], off offset:3584
	v_add_co_u32_e32 v6, vcc, s46, v2
	s_nop 1
	v_addc_co_u32_e32 v7, vcc, 0, v3, vcc
	global_load_ushort v15, v[6:7], off offset:3072
	v_add_co_u32_e32 v6, vcc, s94, v2
	s_nop 1
	v_addc_co_u32_e32 v7, vcc, 0, v3, vcc
	global_load_ushort v16, v[6:7], off offset:2560
	v_add_co_u32_e32 v6, vcc, s95, v2
	s_nop 1
	v_addc_co_u32_e32 v7, vcc, 0, v3, vcc
	global_load_ushort v17, v[6:7], off offset:2048
	v_add_co_u32_e32 v6, vcc, s34, v2
	s_nop 1
	v_addc_co_u32_e32 v7, vcc, 0, v3, vcc
	global_load_ushort v18, v[6:7], off offset:1536
	v_add_co_u32_e32 v6, vcc, s47, v2
	s_nop 1
	v_addc_co_u32_e32 v7, vcc, 0, v3, vcc
	global_load_ushort v19, v[6:7], off offset:1024
	v_add_co_u32_e32 v6, vcc, s35, v2
	s_nop 1
	v_addc_co_u32_e32 v7, vcc, 0, v3, vcc
	global_load_ushort v20, v[6:7], off offset:512
	v_add_co_u32_e32 v6, vcc, s42, v2
	s_nop 1
	v_addc_co_u32_e32 v7, vcc, 0, v3, vcc
	global_load_ushort v21, v[6:7], off
	v_add_co_u32_e32 v6, vcc, s43, v2
	s_nop 1
	v_addc_co_u32_e32 v7, vcc, 0, v3, vcc
	global_load_ushort v22, v[6:7], off offset:3584
	v_add_co_u32_e32 v6, vcc, s54, v2
	s_nop 1
	v_addc_co_u32_e32 v7, vcc, 0, v3, vcc
	global_load_ushort v23, v[6:7], off offset:3072
	v_add_co_u32_e32 v6, vcc, s70, v2
	s_nop 1
	v_addc_co_u32_e32 v7, vcc, 0, v3, vcc
	global_load_ushort v24, v[6:7], off offset:2560
	v_add_co_u32_e32 v6, vcc, s71, v2
	s_nop 1
	v_addc_co_u32_e32 v7, vcc, 0, v3, vcc
	global_load_ushort v25, v[6:7], off offset:2048
	v_add_co_u32_e32 v6, vcc, s74, v2
	s_nop 1
	v_addc_co_u32_e32 v7, vcc, 0, v3, vcc
	global_load_ushort v6, v[6:7], off offset:1536
	s_waitcnt vmcnt(15)
	ds_write_b16 v10, v11 offset:2112
	s_waitcnt vmcnt(14)
	ds_write_b16 v10, v12 offset:2244
	s_waitcnt vmcnt(13)
	ds_write_b16 v10, v13 offset:2376
	s_waitcnt vmcnt(12)
	ds_write_b16 v10, v14 offset:2508
	s_waitcnt vmcnt(11)
	ds_write_b16 v10, v15 offset:2640
	s_waitcnt vmcnt(10)
	ds_write_b16 v10, v16 offset:2772
	s_waitcnt vmcnt(9)
	ds_write_b16 v10, v17 offset:2904
	s_waitcnt vmcnt(8)
	ds_write_b16 v10, v18 offset:3036
	s_waitcnt vmcnt(7)
	ds_write_b16 v10, v19 offset:3168
	s_waitcnt vmcnt(6)
	ds_write_b16 v10, v20 offset:3300
	s_waitcnt vmcnt(5)
	ds_write_b16 v10, v21 offset:3432
	s_waitcnt vmcnt(4)
	ds_write_b16 v10, v22 offset:3564
	s_waitcnt vmcnt(3)
	ds_write_b16 v10, v23 offset:3696
	s_waitcnt vmcnt(2)
	ds_write_b16 v10, v24 offset:3828
	s_waitcnt vmcnt(1)
	ds_write_b16 v10, v25 offset:3960
	s_waitcnt vmcnt(0)
	ds_write_b16 v10, v6 offset:4092
	v_add_co_u32_e32 v6, vcc, s55, v2
	s_nop 1
	v_addc_co_u32_e32 v7, vcc, 0, v3, vcc
	global_load_ushort v11, v[6:7], off offset:1024
	v_add_co_u32_e32 v6, vcc, s1, v2
	s_mov_b32 s1, 0x40000
	s_nop 0
	v_addc_co_u32_e32 v7, vcc, 0, v3, vcc
	global_load_ushort v12, v[6:7], off offset:512
	v_add_co_u32_e32 v6, vcc, s1, v2
	s_mov_b32 s1, 0x41000
	s_nop 0
	v_addc_co_u32_e32 v7, vcc, 0, v3, vcc
	global_load_ushort v13, v[6:7], off
	v_add_co_u32_e32 v6, vcc, s1, v2
	s_mov_b32 s1, 0x45000
	s_nop 0
	v_addc_co_u32_e32 v7, vcc, 0, v3, vcc
	global_load_ushort v14, v[6:7], off offset:3584
	v_add_co_u32_e32 v6, vcc, s56, v2
	s_nop 1
	v_addc_co_u32_e32 v7, vcc, 0, v3, vcc
	global_load_ushort v15, v[6:7], off offset:3072
	v_add_co_u32_e32 v6, vcc, s1, v2
	s_mov_b32 s1, 0x47000
	s_nop 0
	v_addc_co_u32_e32 v7, vcc, 0, v3, vcc
	global_load_ushort v16, v[6:7], off offset:2560
	v_add_co_u32_e32 v6, vcc, s1, v2
	s_mov_b32 s1, 0x49000
	s_nop 0
	v_addc_co_u32_e32 v7, vcc, 0, v3, vcc
	global_load_ushort v17, v[6:7], off offset:2048
	v_add_co_u32_e32 v6, vcc, s1, v2
	s_mov_b32 s1, 0x4d000
	s_nop 0
	v_addc_co_u32_e32 v7, vcc, 0, v3, vcc
	global_load_ushort v18, v[6:7], off offset:1536
	v_add_co_u32_e32 v6, vcc, s57, v2
	s_nop 1
	v_addc_co_u32_e32 v7, vcc, 0, v3, vcc
	global_load_ushort v19, v[6:7], off offset:1024
	v_add_co_u32_e32 v6, vcc, s1, v2
	s_mov_b32 s1, 0x4f000
	s_nop 0
	v_addc_co_u32_e32 v7, vcc, 0, v3, vcc
	global_load_ushort v20, v[6:7], off offset:512
	v_add_co_u32_e32 v6, vcc, s1, v2
	s_mov_b32 s1, 0x50000
	s_nop 0
	v_addc_co_u32_e32 v7, vcc, 0, v3, vcc
	global_load_ushort v21, v[6:7], off
	v_add_co_u32_e32 v6, vcc, s1, v2
	s_mov_b32 s1, 0x54000
	s_nop 0
	v_addc_co_u32_e32 v7, vcc, 0, v3, vcc
	global_load_ushort v22, v[6:7], off offset:3584
	v_add_co_u32_e32 v6, vcc, s58, v2
	s_nop 1
	v_addc_co_u32_e32 v7, vcc, 0, v3, vcc
	global_load_ushort v23, v[6:7], off offset:3072
	v_add_co_u32_e32 v6, vcc, s1, v2
	s_mov_b32 s1, 0x56000
	s_nop 0
	v_addc_co_u32_e32 v7, vcc, 0, v3, vcc
	global_load_ushort v24, v[6:7], off offset:2560
	v_add_co_u32_e32 v6, vcc, s1, v2
	s_mov_b32 s1, 0x58000
	s_nop 0
	v_addc_co_u32_e32 v7, vcc, 0, v3, vcc
	global_load_ushort v25, v[6:7], off offset:2048
	v_add_co_u32_e32 v6, vcc, s1, v2
	s_mov_b32 s1, 0x5c000
	s_nop 0
	v_addc_co_u32_e32 v7, vcc, 0, v3, vcc
	global_load_ushort v6, v[6:7], off offset:1536
	s_waitcnt vmcnt(15)
	ds_write_b16 v10, v11 offset:4224
	s_waitcnt vmcnt(14)
	ds_write_b16 v10, v12 offset:4356
	s_waitcnt vmcnt(13)
	ds_write_b16 v10, v13 offset:4488
	s_waitcnt vmcnt(12)
	ds_write_b16 v10, v14 offset:4620
	s_waitcnt vmcnt(11)
	ds_write_b16 v10, v15 offset:4752
	s_waitcnt vmcnt(10)
	ds_write_b16 v10, v16 offset:4884
	s_waitcnt vmcnt(9)
	ds_write_b16 v10, v17 offset:5016
	s_waitcnt vmcnt(8)
	ds_write_b16 v10, v18 offset:5148
	s_waitcnt vmcnt(7)
	ds_write_b16 v10, v19 offset:5280
	s_waitcnt vmcnt(6)
	ds_write_b16 v10, v20 offset:5412
	s_waitcnt vmcnt(5)
	ds_write_b16 v10, v21 offset:5544
	s_waitcnt vmcnt(4)
	ds_write_b16 v10, v22 offset:5676
	s_waitcnt vmcnt(3)
	ds_write_b16 v10, v23 offset:5808
	s_waitcnt vmcnt(2)
	ds_write_b16 v10, v24 offset:5940
	s_waitcnt vmcnt(1)
	ds_write_b16 v10, v25 offset:6072
	s_waitcnt vmcnt(0)
	ds_write_b16 v10, v6 offset:6204
	v_add_co_u32_e32 v6, vcc, s59, v2
	s_nop 1
	v_addc_co_u32_e32 v7, vcc, 0, v3, vcc
	global_load_ushort v11, v[6:7], off offset:1024
	v_add_co_u32_e32 v6, vcc, s1, v2
	s_mov_b32 s1, 0x5e000
	s_nop 0
	v_addc_co_u32_e32 v7, vcc, 0, v3, vcc
	global_load_ushort v12, v[6:7], off offset:512
	v_add_co_u32_e32 v6, vcc, s1, v2
	s_mov_b32 s1, 0x5f000
	s_nop 0
	v_addc_co_u32_e32 v7, vcc, 0, v3, vcc
	global_load_ushort v13, v[6:7], off
	v_add_co_u32_e32 v6, vcc, s1, v2
	s_mov_b32 s1, 0x63000
	s_nop 0
	v_addc_co_u32_e32 v7, vcc, 0, v3, vcc
	global_load_ushort v14, v[6:7], off offset:3584
	v_add_co_u32_e32 v6, vcc, s60, v2
	s_nop 1
	v_addc_co_u32_e32 v7, vcc, 0, v3, vcc
	global_load_ushort v15, v[6:7], off offset:3072
	v_add_co_u32_e32 v6, vcc, s1, v2
	s_mov_b32 s1, 0x65000
	s_nop 0
	v_addc_co_u32_e32 v7, vcc, 0, v3, vcc
	global_load_ushort v16, v[6:7], off offset:2560
	v_add_co_u32_e32 v6, vcc, s1, v2
	s_mov_b32 s1, 0x67000
	s_nop 0
	v_addc_co_u32_e32 v7, vcc, 0, v3, vcc
	global_load_ushort v17, v[6:7], off offset:2048
	v_add_co_u32_e32 v6, vcc, s1, v2
	s_mov_b32 s1, 0x6b000
	s_nop 0
	v_addc_co_u32_e32 v7, vcc, 0, v3, vcc
	global_load_ushort v18, v[6:7], off offset:1536
	v_add_co_u32_e32 v6, vcc, s12, v2
	s_nop 1
	v_addc_co_u32_e32 v7, vcc, 0, v3, vcc
	global_load_ushort v19, v[6:7], off offset:1024
	v_add_co_u32_e32 v6, vcc, s1, v2
	s_mov_b32 s1, 0x6d000
	s_nop 0
	v_addc_co_u32_e32 v7, vcc, 0, v3, vcc
	global_load_ushort v20, v[6:7], off offset:512
	v_add_co_u32_e32 v6, vcc, s1, v2
	s_mov_b32 s1, 0x6e000
	s_nop 0
	v_addc_co_u32_e32 v7, vcc, 0, v3, vcc
	global_load_ushort v21, v[6:7], off
	v_add_co_u32_e32 v6, vcc, s1, v2
	s_mov_b32 s1, 0x72000
	s_nop 0
	v_addc_co_u32_e32 v7, vcc, 0, v3, vcc
	global_load_ushort v22, v[6:7], off offset:3584
	v_add_co_u32_e32 v6, vcc, s13, v2
	s_nop 1
	v_addc_co_u32_e32 v7, vcc, 0, v3, vcc
	global_load_ushort v23, v[6:7], off offset:3072
	v_add_co_u32_e32 v6, vcc, s1, v2
	s_mov_b32 s1, 0x74000
	s_nop 0
	v_addc_co_u32_e32 v7, vcc, 0, v3, vcc
	global_load_ushort v24, v[6:7], off offset:2560
	v_add_co_u32_e32 v6, vcc, s1, v2
	s_mov_b32 s1, 0x76000
	s_nop 0
	v_addc_co_u32_e32 v7, vcc, 0, v3, vcc
	v_add_co_u32_e32 v2, vcc, s1, v2
	global_load_ushort v6, v[6:7], off offset:2048
	s_nop 0
	v_addc_co_u32_e32 v3, vcc, 0, v3, vcc
	global_load_ushort v2, v[2:3], off offset:1536
	s_waitcnt vmcnt(15)
	ds_write_b16 v10, v11 offset:6336
	s_waitcnt vmcnt(14)
	ds_write_b16 v10, v12 offset:6468
	s_waitcnt vmcnt(13)
	ds_write_b16 v10, v13 offset:6600
	s_waitcnt vmcnt(12)
	ds_write_b16 v10, v14 offset:6732
	s_waitcnt vmcnt(11)
	ds_write_b16 v10, v15 offset:6864
	s_waitcnt vmcnt(10)
	ds_write_b16 v10, v16 offset:6996
	s_waitcnt vmcnt(9)
	ds_write_b16 v10, v17 offset:7128
	s_waitcnt vmcnt(8)
	ds_write_b16 v10, v18 offset:7260
	s_waitcnt vmcnt(7)
	ds_write_b16 v10, v19 offset:7392
	s_waitcnt vmcnt(6)
	ds_write_b16 v10, v20 offset:7524
	s_waitcnt vmcnt(5)
	ds_write_b16 v10, v21 offset:7656
	s_waitcnt vmcnt(4)
	ds_write_b16 v10, v22 offset:7788
	s_waitcnt vmcnt(3)
	ds_write_b16 v10, v23 offset:7920
	s_waitcnt vmcnt(2)
	ds_write_b16 v10, v24 offset:8052
	s_waitcnt vmcnt(1)
	ds_write_b16 v10, v6 offset:8184
	s_waitcnt vmcnt(0)
	ds_write_b16 v10, v2 offset:8316
	s_waitcnt lgkmcnt(0)
	s_ashr_i32 s1, s0, 31
	s_lshl_b64 s[0:1], s[0:1], 18
	v_mbcnt_lo_u32_b32 v6, -1, 0
	v_mbcnt_hi_u32_b32 v6, -1, v6
	v_lshrrev_b32_e32 v6, 5, v6
	v_mul_u32_u24_e32 v6, 0xfc0, v6
	v_mov_b32_e32 v7, 0
	v_lshl_add_u64 v[2:3], v[0:1], 0, s[0:1]
	v_lshl_add_u64 v[2:3], v[2:3], 0, v[6:7]
	s_lshl_b32 s0, s44, 6
	s_mov_b32 s1, 0
	v_lshl_add_u64 v[2:3], v[2:3], 0, s[0:1]
	s_cmpk_gt_i32 s6, 0x3ff
	ds_read2_b32 v[12:13], v9 offset0:0 offset1:1
	ds_read2_b32 v[14:15], v9 offset0:2 offset1:3
	ds_read2_b32 v[16:17], v9 offset0:4 offset1:5
	ds_read2_b32 v[18:19], v9 offset0:6 offset1:7
	s_waitcnt lgkmcnt(0)
	global_store_short v[2:3], v12, off offset:0
	global_store_short_d16_hi v[2:3], v12, off offset:64
	global_store_short v[2:3], v13, off offset:128
	global_store_short_d16_hi v[2:3], v13, off offset:192
	global_store_short v[2:3], v14, off offset:256
	global_store_short_d16_hi v[2:3], v14, off offset:320
	global_store_short v[2:3], v15, off offset:384
	global_store_short_d16_hi v[2:3], v15, off offset:448
	global_store_short v[2:3], v16, off offset:512
	global_store_short_d16_hi v[2:3], v16, off offset:576
	global_store_short v[2:3], v17, off offset:640
	global_store_short_d16_hi v[2:3], v17, off offset:704
	global_store_short v[2:3], v18, off offset:768
	global_store_short_d16_hi v[2:3], v18, off offset:832
	global_store_short v[2:3], v19, off offset:896
	global_store_short_d16_hi v[2:3], v19, off offset:960
	ds_read2_b32 v[12:13], v9 offset0:8 offset1:9
	ds_read2_b32 v[14:15], v9 offset0:10 offset1:11
	ds_read2_b32 v[16:17], v9 offset0:12 offset1:13
	ds_read2_b32 v[18:19], v9 offset0:14 offset1:15
	s_waitcnt lgkmcnt(0)
	global_store_short v[2:3], v12, off offset:1024
	global_store_short_d16_hi v[2:3], v12, off offset:1088
	global_store_short v[2:3], v13, off offset:1152
	global_store_short_d16_hi v[2:3], v13, off offset:1216
	global_store_short v[2:3], v14, off offset:1280
	global_store_short_d16_hi v[2:3], v14, off offset:1344
	global_store_short v[2:3], v15, off offset:1408
	global_store_short_d16_hi v[2:3], v15, off offset:1472
	global_store_short v[2:3], v16, off offset:1536
	global_store_short_d16_hi v[2:3], v16, off offset:1600
	global_store_short v[2:3], v17, off offset:1664
	global_store_short_d16_hi v[2:3], v17, off offset:1728
	global_store_short v[2:3], v18, off offset:1792
	global_store_short_d16_hi v[2:3], v18, off offset:1856
	global_store_short v[2:3], v19, off offset:1920
	global_store_short_d16_hi v[2:3], v19, off offset:1984
	ds_read2_b32 v[12:13], v9 offset0:16 offset1:17
	ds_read2_b32 v[14:15], v9 offset0:18 offset1:19
	ds_read2_b32 v[16:17], v9 offset0:20 offset1:21
	ds_read2_b32 v[18:19], v9 offset0:22 offset1:23
	s_waitcnt lgkmcnt(0)
	global_store_short v[2:3], v12, off offset:2048
	global_store_short_d16_hi v[2:3], v12, off offset:2112
	global_store_short v[2:3], v13, off offset:2176
	global_store_short_d16_hi v[2:3], v13, off offset:2240
	global_store_short v[2:3], v14, off offset:2304
	global_store_short_d16_hi v[2:3], v14, off offset:2368
	global_store_short v[2:3], v15, off offset:2432
	global_store_short_d16_hi v[2:3], v15, off offset:2496
	global_store_short v[2:3], v16, off offset:2560
	global_store_short_d16_hi v[2:3], v16, off offset:2624
	global_store_short v[2:3], v17, off offset:2688
	global_store_short_d16_hi v[2:3], v17, off offset:2752
	global_store_short v[2:3], v18, off offset:2816
	global_store_short_d16_hi v[2:3], v18, off offset:2880
	global_store_short v[2:3], v19, off offset:2944
	global_store_short_d16_hi v[2:3], v19, off offset:3008
	ds_read2_b32 v[12:13], v9 offset0:24 offset1:25
	ds_read2_b32 v[14:15], v9 offset0:26 offset1:27
	ds_read2_b32 v[16:17], v9 offset0:28 offset1:29
	ds_read2_b32 v[18:19], v9 offset0:30 offset1:31
	s_waitcnt lgkmcnt(0)
	global_store_short v[2:3], v12, off offset:3072
	global_store_short_d16_hi v[2:3], v12, off offset:3136
	global_store_short v[2:3], v13, off offset:3200
	global_store_short_d16_hi v[2:3], v13, off offset:3264
	global_store_short v[2:3], v14, off offset:3328
	global_store_short_d16_hi v[2:3], v14, off offset:3392
	global_store_short v[2:3], v15, off offset:3456
	global_store_short_d16_hi v[2:3], v15, off offset:3520
	global_store_short v[2:3], v16, off offset:3584
	global_store_short_d16_hi v[2:3], v16, off offset:3648
	global_store_short v[2:3], v17, off offset:3712
	global_store_short_d16_hi v[2:3], v17, off offset:3776
	global_store_short v[2:3], v18, off offset:3840
	global_store_short_d16_hi v[2:3], v18, off offset:3904
	global_store_short v[2:3], v19, off offset:3968
	global_store_short_d16_hi v[2:3], v19, off offset:4032
	s_waitcnt lgkmcnt(0)
	s_cbranch_scc0 .LBB0_422

.LBB0_836:
	v_readlane_b32 s35, v253, 32
	s_lshl_b32 s44, s35, 6
	s_waitcnt vmcnt(0)
	v_mov_b32_e32 v2, v179
	s_lshl_b64 s[22:23], s[44:45], 2
	v_readlane_b32 s0, v251, 38
	s_add_u32 s40, s0, s22
	v_readlane_b32 s0, v251, 39
	v_bfe_u32 v1, v2, 4, 2
	v_readlane_b32 s10, v250, 59
	v_readlane_b32 s48, v249, 8
	v_and_b32_e32 v0, 63, v2
	s_addc_u32 s41, s0, s23
	v_and_b32_e32 v32, 15, v2
	v_lshlrev_b32_e32 v34, 3, v1
	v_mov_b32_e32 v35, v157
	v_readlane_b32 s11, v250, 60
	v_readlane_b32 s52, v249, 12
	v_cmp_eq_u32_e64 s[0:1], 0, v0
	v_lshlrev_b32_e32 v36, 2, v1
	v_cmp_eq_u32_e64 s[4:5], 3, v1
	v_cmp_gt_u32_e64 s[6:7], 32, v0
	v_cmp_gt_u32_e64 s[8:9], 16, v0
	v_lshlrev_b32_e32 v156, 6, v32
	v_lshl_add_u64 v[0:1], s[10:11], 0, v[34:35]
	v_readlane_b32 s49, v249, 9
	v_readlane_b32 s50, v249, 10
	v_readlane_b32 s51, v249, 11
	v_readlane_b32 s53, v249, 13
	v_readlane_b32 s56, v249, 16
	v_readlane_b32 s57, v249, 17
	v_readlane_b32 s60, v249, 20
	v_readlane_b32 s61, v249, 21
	s_add_u32 s10, s52, s22
	v_lshl_add_u64 v[38:39], v[0:1], 0, v[156:157]
	v_readlane_b32 s54, v249, 14
	v_readlane_b32 s55, v249, 15
	v_readlane_b32 s62, v249, 22
	s_addc_u32 s11, s53, s23
	v_and_b32_e32 v156, 48, v2
	v_readlane_b32 s60, v253, 17
	v_readlane_b32 s88, v253, 19
	v_readlane_b32 s50, v253, 21
	v_readlane_b32 s48, v253, 23
	v_readlane_b32 s52, v253, 25
	v_readlane_b32 s56, v249, 51
	v_readlane_b32 s70, v253, 37
	v_readlane_b32 s74, v253, 35
	v_readlane_b32 s94, v253, 33
	v_lshl_add_u64 v[40:41], s[10:11], 0, v[156:157]
	v_readlane_b32 s61, v253, 18
	v_readlane_b32 s89, v253, 20
	v_readlane_b32 s51, v253, 22
	v_readlane_b32 s49, v253, 24
	v_readlane_b32 s53, v253, 26
	v_readlane_b32 s57, v249, 52
	v_readlane_b32 s62, v253, 27
	s_mov_b64 s[54:55], 0x1200
	v_readlane_b32 s71, v253, 38
	v_readlane_b32 s75, v253, 36
	v_readlane_b32 s95, v253, 34
	v_readlane_b32 s58, v249, 18
	v_readlane_b32 s59, v249, 19
	v_readlane_b32 s63, v249, 23
	s_branch .LBB0_838

.LBB0_844:
	s_mov_b32 s59, s45
	v_lshl_add_u64 v[24:25], v[44:45], 0, s[58:59]
	v_mov_b64_e32 v[26:27], s[20:21]
	v_mad_u64_u32 v[26:27], s[10:11], v24, s90, v[26:27]
	v_mad_i32_i24 v27, v25, s90, v27
	s_lshl_b32 s44, s46, 1
	v_lshl_add_u64 v[24:25], v[26:27], 0, s[44:45]
	v_lshl_add_u64 v[48:49], v[24:25], 0, v[156:157]
	v_add_co_u32_e32 v24, vcc, s76, v48
	s_mov_b64 s[10:11], 0x1e200
	s_nop 0
	v_addc_co_u32_e32 v25, vcc, 0, v49, vcc
	global_load_dwordx4 v[24:27], v[24:25], off offset:512
	v_lshl_add_u64 v[30:31], v[48:49], 0, s[10:11]
	global_load_dwordx4 v[52:55], v[30:31], off offset:64
	global_load_dwordx4 v[58:61], v[48:49], off offset:576
	global_load_dwordx4 v[96:99], v[48:49], off offset:512
	s_lshl_b32 s10, s58, 7
	s_mov_b32 s11, 0
	v_lshl_add_u64 v[116:117], v[46:47], 0, s[10:11]
	global_load_dwordx2 v[100:101], v[116:117], off
	global_load_dwordx2 v[102:103], v[116:117], off offset:32
	global_load_dwordx2 v[104:105], v[116:117], off offset:1024
	global_load_dwordx2 v[106:107], v[116:117], off offset:1056
	global_load_dwordx2 v[108:109], v[116:117], off offset:2048
	global_load_dwordx2 v[110:111], v[116:117], off offset:2080
	global_load_dwordx2 v[112:113], v[116:117], off offset:3072
	global_load_dwordx2 v[114:115], v[116:117], off offset:3104
	v_add_u32_e32 v29, s58, v36
	v_add_u32_e32 v30, 16, v29
	v_cmp_lt_u32_e32 vcc, v30, v33
	s_waitcnt vmcnt(11)
	v_mfma_f32_16x16x32_bf16 v[24:27], v[24:27], v[16:19], 0
	s_waitcnt vmcnt(10)
	v_mfma_f32_16x16x32_bf16 v[24:27], v[52:55], v[20:23], v[24:27]
	s_nop 7
	v_mul_f32_e32 v31, 0x3e000000, v24
	v_max_f32_e32 v30, 0, v31
	v_mul_f32_e64 v31, |v31|, s83
	v_exp_f32_e32 v31, v31
	s_nop 0
	v_add_f32_e32 v31, 1.0, v31
	v_cmp_gt_f32_e64 s[10:11], s93, v31
	s_nop 1
	v_cndmask_b32_e64 v52, 0, 32, s[10:11]
	v_ldexp_f32 v31, v31, v52
	v_log_f32_e32 v31, v31
	s_nop 0
	v_mul_f32_e32 v52, 0x3f317217, v31
	v_fma_f32 v52, v31, s96, -v52
	v_fmac_f32_e32 v52, 0x3377d1cf, v31
	v_fmac_f32_e32 v52, 0x3f317217, v31
	v_cmp_lt_f32_e64 s[12:13], |v31|, s77
	s_nop 1
	v_cndmask_b32_e64 v31, v31, v52, s[12:13]
	v_cndmask_b32_e64 v52, 0, v224, s[10:11]
	v_sub_f32_e32 v31, v31, v52
	v_add_f32_e32 v30, v30, v31
	v_cndmask_b32_e64 v31, 0, -v30, vcc
	v_fma_f32 v24, v24, s97, -v30
	v_mul_f32_e32 v30, 0x3e000000, v25
	v_add_u32_e32 v52, 17, v29
	v_cmp_lt_u32_e64 s[10:11], v52, v33
	v_max_f32_e32 v52, 0, v30
	v_mul_f32_e64 v30, |v30|, s83
	v_exp_f32_e32 v30, v30
	s_nop 0
	v_add_f32_e32 v30, 1.0, v30
	v_cmp_gt_f32_e64 s[12:13], s93, v30
	s_nop 1
	v_cndmask_b32_e64 v53, 0, 32, s[12:13]
	v_ldexp_f32 v30, v30, v53
	v_log_f32_e32 v30, v30
	s_nop 0
	v_mul_f32_e32 v53, 0x3f317217, v30
	v_fma_f32 v53, v30, s96, -v53
	v_fmac_f32_e32 v53, 0x3377d1cf, v30
	v_fmac_f32_e32 v53, 0x3f317217, v30
	v_cmp_lt_f32_e64 s[14:15], |v30|, s77
	s_nop 1
	v_cndmask_b32_e64 v30, v30, v53, s[14:15]
	v_cndmask_b32_e64 v53, 0, v224, s[12:13]
	v_sub_f32_e32 v30, v30, v53
	v_add_f32_e32 v30, v52, v30
	v_cndmask_b32_e64 v52, 0, -v30, s[10:11]
	v_fma_f32 v25, v25, s97, -v30
	v_mul_f32_e32 v30, 0x3e000000, v26
	v_add_u32_e32 v53, 18, v29
	v_cmp_lt_u32_e64 s[12:13], v53, v33
	v_max_f32_e32 v53, 0, v30
	v_mul_f32_e64 v30, |v30|, s83
	v_exp_f32_e32 v30, v30
	s_nop 0
	v_add_f32_e32 v30, 1.0, v30
	v_cmp_gt_f32_e64 s[14:15], s93, v30
	s_nop 1
	v_cndmask_b32_e64 v54, 0, 32, s[14:15]
	v_ldexp_f32 v30, v30, v54
	v_log_f32_e32 v30, v30
	s_nop 0
	v_mul_f32_e32 v54, 0x3f317217, v30
	v_fma_f32 v54, v30, s96, -v54
	v_fmac_f32_e32 v54, 0x3377d1cf, v30
	v_fmac_f32_e32 v54, 0x3f317217, v30
	v_cmp_lt_f32_e64 s[16:17], |v30|, s77
	s_nop 1
	v_cndmask_b32_e64 v30, v30, v54, s[16:17]
	v_cndmask_b32_e64 v54, 0, v224, s[14:15]
	v_sub_f32_e32 v30, v30, v54
	v_add_f32_e32 v30, v53, v30
	v_cndmask_b32_e64 v53, 0, -v30, s[12:13]
	v_fma_f32 v26, v26, s97, -v30
	v_mul_f32_e32 v30, 0x3e000000, v27
	v_add_u32_e32 v54, 19, v29
	v_cmp_lt_u32_e64 s[14:15], v54, v33
	v_max_f32_e32 v54, 0, v30
	v_mul_f32_e64 v30, |v30|, s83
	v_exp_f32_e32 v30, v30
	s_nop 0
	v_add_f32_e32 v30, 1.0, v30
	v_cmp_gt_f32_e64 s[16:17], s93, v30
	s_nop 1
	v_cndmask_b32_e64 v55, 0, 32, s[16:17]
	v_ldexp_f32 v30, v30, v55
	v_log_f32_e32 v30, v30
	s_nop 0
	v_mul_f32_e32 v55, 0x3f317217, v30
	v_fma_f32 v55, v30, s96, -v55
	v_fmac_f32_e32 v55, 0x3377d1cf, v30
	v_fmac_f32_e32 v55, 0x3f317217, v30
	v_cmp_lt_f32_e64 s[18:19], |v30|, s77
	s_nop 1
	v_cndmask_b32_e64 v30, v30, v55, s[18:19]
	v_cndmask_b32_e64 v55, 0, v224, s[16:17]
	v_sub_f32_e32 v30, v30, v55
	v_add_f32_e32 v30, v54, v30
	v_cndmask_b32_e64 v55, 0, -v30, s[14:15]
	v_add_f32_e32 v54, v55, v53
	v_add_f32_e32 v52, v52, v54
	v_fma_f32 v27, v27, s97, -v30
	v_add_f32_e32 v30, v31, v52
	ds_bpermute_b32 v31, v35, v30
	ds_bpermute_b32 v53, v37, v30
	ds_bpermute_b32 v56, v50, v30
	s_waitcnt lgkmcnt(2)
	v_cndmask_b32_e64 v31, v31, 0, s[4:5]
	s_waitcnt lgkmcnt(1)
	v_cndmask_b32_e64 v53, 0, v53, s[6:7]
	v_add_f32_e32 v31, v31, v53
	s_waitcnt lgkmcnt(0)
	v_cndmask_b32_e64 v53, 0, v56, s[8:9]
	v_add_f32_e32 v31, v31, v53
	v_add_f32_e32 v30, v31, v30
	v_add_f32_e32 v31, v28, v31
	v_add_f32_e32 v24, v31, v24
	v_add_f32_e32 v24, v24, v52
	v_mul_f32_e32 v24, 0x3fb8aa3b, v24
	v_exp_f32_e32 v24, v24
	ds_bpermute_b32 v30, v51, v30
	v_cndmask_b32_e32 v53, 0, v24, vcc
	v_add_f32_e32 v24, v31, v25
	v_add_f32_e32 v24, v54, v24
	v_mul_f32_e32 v24, 0x3fb8aa3b, v24
	v_exp_f32_e32 v24, v24
	v_cmp_lt_u32_e32 vcc, v29, v33
	v_cndmask_b32_e64 v54, 0, v24, s[10:11]
	v_add_f32_e32 v24, v31, v26
	v_add_f32_e32 v24, v55, v24
	v_mul_f32_e32 v24, 0x3fb8aa3b, v24
	v_exp_f32_e32 v24, v24
	s_nop 0
	v_cndmask_b32_e64 v55, 0, v24, s[12:13]
	v_add_f32_e32 v24, v31, v27
	v_mul_f32_e32 v24, 0x3fb8aa3b, v24
	v_exp_f32_e32 v24, v24
	s_nop 0
	v_cndmask_b32_e64 v56, 0, v24, s[14:15]
	s_waitcnt vmcnt(8)
	v_mfma_f32_16x16x32_bf16 v[24:27], v[96:99], v[16:19], 0
	v_mfma_f32_16x16x32_bf16 v[24:27], v[58:61], v[20:23], v[24:27]
	s_nop 7
	v_mul_f32_e32 v31, 0x3e000000, v24
	v_max_f32_e32 v48, 0, v31
	v_mul_f32_e64 v31, |v31|, s83
	v_exp_f32_e32 v31, v31
	s_nop 0
	v_add_f32_e32 v31, 1.0, v31
	v_cmp_gt_f32_e64 s[10:11], s93, v31
	s_nop 1
	v_cndmask_b32_e64 v49, 0, 32, s[10:11]
	v_ldexp_f32 v31, v31, v49
	v_log_f32_e32 v31, v31
	s_nop 0
	v_mul_f32_e32 v49, 0x3f317217, v31
	v_fma_f32 v49, v31, s96, -v49
	v_fmac_f32_e32 v49, 0x3377d1cf, v31
	v_fmac_f32_e32 v49, 0x3f317217, v31
	v_cmp_lt_f32_e64 s[12:13], |v31|, s77
	s_nop 1
	v_cndmask_b32_e64 v31, v31, v49, s[12:13]
	v_cndmask_b32_e64 v49, 0, v224, s[10:11]
	v_sub_f32_e32 v31, v31, v49
	v_add_f32_e32 v48, v48, v31
	v_cndmask_b32_e64 v31, 0, -v48, vcc
	v_fma_f32 v24, v24, s97, -v48
	v_mul_f32_e32 v48, 0x3e000000, v25
	v_add_u32_e32 v49, 1, v29
	v_cmp_lt_u32_e64 s[10:11], v49, v33
	v_max_f32_e32 v49, 0, v48
	v_mul_f32_e64 v48, |v48|, s83
	v_exp_f32_e32 v48, v48
	s_nop 0
	v_add_f32_e32 v48, 1.0, v48
	v_cmp_gt_f32_e64 s[12:13], s93, v48
	s_nop 1
	v_cndmask_b32_e64 v52, 0, 32, s[12:13]
	v_ldexp_f32 v48, v48, v52
	v_log_f32_e32 v48, v48
	s_nop 0
	v_mul_f32_e32 v52, 0x3f317217, v48
	v_fma_f32 v52, v48, s96, -v52
	v_fmac_f32_e32 v52, 0x3377d1cf, v48
	v_fmac_f32_e32 v52, 0x3f317217, v48
	v_cmp_lt_f32_e64 s[14:15], |v48|, s77
	s_nop 1
	v_cndmask_b32_e64 v48, v48, v52, s[14:15]
	v_cndmask_b32_e64 v52, 0, v224, s[12:13]
	v_sub_f32_e32 v48, v48, v52
	v_add_f32_e32 v48, v49, v48
	v_cndmask_b32_e64 v49, 0, -v48, s[10:11]
	v_fma_f32 v25, v25, s97, -v48
	v_mul_f32_e32 v48, 0x3e000000, v26
	v_add_u32_e32 v52, 2, v29
	v_cmp_lt_u32_e64 s[12:13], v52, v33
	v_max_f32_e32 v52, 0, v48
	v_mul_f32_e64 v48, |v48|, s83
	v_exp_f32_e32 v48, v48
	v_add_u32_e32 v29, 3, v29
	v_add_f32_e32 v48, 1.0, v48
	v_cmp_gt_f32_e64 s[14:15], s93, v48
	s_nop 1
	v_cndmask_b32_e64 v57, 0, 32, s[14:15]
	v_ldexp_f32 v48, v48, v57
	v_log_f32_e32 v48, v48
	s_nop 0
	v_mul_f32_e32 v57, 0x3f317217, v48
	v_fma_f32 v57, v48, s96, -v57
	v_fmac_f32_e32 v57, 0x3377d1cf, v48
	v_fmac_f32_e32 v57, 0x3f317217, v48
	v_cmp_lt_f32_e64 s[16:17], |v48|, s77
	s_nop 1
	v_cndmask_b32_e64 v48, v48, v57, s[16:17]
	v_cndmask_b32_e64 v57, 0, v224, s[14:15]
	v_sub_f32_e32 v48, v48, v57
	v_add_f32_e32 v48, v52, v48
	v_cndmask_b32_e64 v52, 0, -v48, s[12:13]
	v_fma_f32 v26, v26, s97, -v48
	v_mul_f32_e32 v48, 0x3e000000, v27
	v_cmp_lt_u32_e64 s[14:15], v29, v33
	v_max_f32_e32 v29, 0, v48
	v_mul_f32_e64 v48, |v48|, s83
	v_exp_f32_e32 v48, v48
	s_nop 0
	v_add_f32_e32 v48, 1.0, v48
	v_cmp_gt_f32_e64 s[16:17], s93, v48
	s_nop 1
	v_cndmask_b32_e64 v57, 0, 32, s[16:17]
	v_ldexp_f32 v48, v48, v57
	v_log_f32_e32 v48, v48
	s_nop 0
	v_mul_f32_e32 v57, 0x3f317217, v48
	v_fma_f32 v57, v48, s96, -v57
	v_fmac_f32_e32 v57, 0x3377d1cf, v48
	v_fmac_f32_e32 v57, 0x3f317217, v48
	v_cmp_lt_f32_e64 s[18:19], |v48|, s77
	s_nop 1
	v_cndmask_b32_e64 v48, v48, v57, s[18:19]
	v_cndmask_b32_e64 v57, 0, v224, s[16:17]
	v_sub_f32_e32 v48, v48, v57
	v_add_f32_e32 v29, v29, v48
	v_cndmask_b32_e64 v57, 0, -v29, s[14:15]
	v_add_f32_e32 v58, v57, v52
	v_add_f32_e32 v59, v49, v58
	v_add_f32_e32 v52, v31, v59
	v_fma_f32 v27, v27, s97, -v29
	ds_bpermute_b32 v29, v35, v52
	ds_bpermute_b32 v31, v37, v52
	ds_bpermute_b32 v48, v50, v52
	s_waitcnt lgkmcnt(2)
	v_cndmask_b32_e64 v29, v29, 0, s[4:5]
	s_waitcnt lgkmcnt(1)
	v_cndmask_b32_e64 v31, 0, v31, s[6:7]
	v_add_f32_e32 v29, v29, v31
	s_waitcnt lgkmcnt(0)
	v_cndmask_b32_e64 v31, 0, v48, s[8:9]
	v_pk_add_f32 v[48:49], v[28:29], v[30:31]
	s_nop 0
	v_add_f32_e32 v28, v49, v52
	ds_bpermute_b32 v52, v51, v28
	v_add_f32_e32 v28, v48, v49
	v_add_f32_e32 v24, v28, v24
	v_add_f32_e32 v25, v28, v25
	v_add_f32_e32 v26, v28, v26
	v_add_f32_e32 v24, v24, v59
	v_add_f32_e32 v25, v58, v25
	v_add_f32_e32 v26, v57, v26
	v_add_f32_e32 v27, v28, v27
	v_mul_f32_e32 v24, 0x3fb8aa3b, v24
	v_mul_f32_e32 v25, 0x3fb8aa3b, v25
	v_mul_f32_e32 v26, 0x3fb8aa3b, v26
	v_mul_f32_e32 v27, 0x3fb8aa3b, v27
	v_exp_f32_e32 v24, v24
	v_exp_f32_e32 v25, v25
	v_exp_f32_e32 v26, v26
	v_exp_f32_e32 v27, v27
	v_cndmask_b32_e32 v24, 0, v24, vcc
	v_cndmask_b32_e64 v25, 0, v25, s[10:11]
	v_cndmask_b32_e64 v26, 0, v26, s[12:13]
	v_cndmask_b32_e64 v27, 0, v27, s[14:15]
	v_cvt_pk_bf16_f32 v24, v24, v25
	v_cvt_pk_bf16_f32 v25, v26, v27
	v_cvt_pk_bf16_f32 v26, v53, v54
	v_cvt_pk_bf16_f32 v27, v55, v56
	s_mov_b32 s10, 0xc2b40000
	s_nop 1
	s_waitcnt vmcnt(6)
	v_mfma_f32_16x16x32_bf16 v[12:15], v[100:103], v[24:27], v[12:15]
	s_waitcnt vmcnt(4)
	v_mfma_f32_16x16x32_bf16 v[8:11], v[104:107], v[24:27], v[8:11]
	s_waitcnt vmcnt(2)
	v_mfma_f32_16x16x32_bf16 v[4:7], v[108:111], v[24:27], v[4:7]
	s_waitcnt vmcnt(0)
	v_mfma_f32_16x16x32_bf16 v[0:3], v[112:115], v[24:27], v[0:3]
	s_waitcnt lgkmcnt(0)
	v_add_f32_e32 v28, v48, v52
	v_cmp_gt_f32_e32 vcc, s10, v28
	s_cmp_lg_u64 vcc, exec
	s_cselect_b64 s[10:11], -1, 0
	s_cmp_lg_u32 s58, 0
	s_cselect_b64 s[12:13], -1, 0
	s_and_b64 s[10:11], s[12:13], s[10:11]
	s_sub_i32 s58, s58, 32
	s_and_b64 vcc, exec, s[10:11]
	s_cbranch_vccnz .LBB0_844
	v_pk_mul_f32 v[16:17], v[14:15], v[14:15]
	v_pk_mul_f32 v[18:19], v[12:13], v[12:13]
	v_lshlrev_b32_e32 v156, 1, v36
	v_pk_mov_b32 v[20:21], v[18:19], v[16:17] op_sel:[1,0]
	v_mov_b32_e32 v19, v17
	v_pk_add_f32 v[16:17], v[20:21], v[18:19]
	v_pk_mul_f32 v[18:19], v[10:11], v[10:11]
	v_pk_mul_f32 v[20:21], v[8:9], v[8:9]
	v_pk_add_f32 v[16:17], v[16:17], v[16:17] op_sel:[0,1] op_sel_hi:[1,0]
	v_pk_mov_b32 v[22:23], v[20:21], v[18:19] op_sel:[1,0]
	v_mov_b32_e32 v21, v19
	v_pk_add_f32 v[18:19], v[22:23], v[20:21]
	v_mul_f32_e32 v20, v0, v0
	v_mul_f32_e32 v21, v1, v1
	v_pk_add_f32 v[18:19], v[18:19], v[18:19] op_sel:[0,1] op_sel_hi:[1,0]
	v_mov_b32_e32 v17, v20
	v_mov_b32_e32 v19, v21
	v_pk_add_f32 v[16:17], v[16:17], v[18:19]
	v_mul_f32_e32 v18, v5, v5
	v_mul_f32_e32 v20, v7, v7
	v_mul_f32_e32 v22, v2, v2
	v_mul_f32_e32 v23, v3, v3
	v_pk_fma_f32 v[18:19], v[4:5], v[4:5], v[18:19] op_sel_hi:[1,1,0]
	v_pk_fma_f32 v[20:21], v[6:7], v[6:7], v[20:21] op_sel_hi:[1,1,0]
	v_mov_b32_e32 v19, v22
	v_mov_b32_e32 v21, v23
	v_pk_add_f32 v[18:19], v[18:19], v[20:21]
	global_load_dwordx4 v[20:23], v[40:41], off
	v_pk_add_f32 v[16:17], v[16:17], v[18:19]
	v_and_b32_e32 v18, 64, v217
	v_add_f32_e32 v16, v16, v17
	v_xor_b32_e32 v17, 16, v217
	v_add_u32_e32 v18, 64, v18
	v_cmp_lt_i32_e32 vcc, v17, v18
	s_mov_b64 s[10:11], 0
	s_nop 0
	v_cndmask_b32_e32 v17, v217, v17, vcc
	v_lshlrev_b32_e32 v17, 2, v17
	ds_bpermute_b32 v17, v17, v16
	s_waitcnt lgkmcnt(0)
	v_add_f32_e32 v16, v16, v17
	v_xor_b32_e32 v17, 32, v217
	v_cmp_lt_i32_e32 vcc, v17, v18
	s_nop 1
	v_cndmask_b32_e32 v17, v217, v17, vcc
	v_lshlrev_b32_e32 v17, 2, v17
	ds_bpermute_b32 v17, v17, v16
	s_waitcnt lgkmcnt(0)
	v_add_f32_e32 v16, v16, v17
	v_fmamk_f32 v16, v16, 0x3c800000, v212
	v_rsq_f32_e32 v18, v16
	v_lshlrev_b64 v[16:17], 11, v[42:43]
	v_lshl_add_u64 v[16:17], s[36:37], 0, v[16:17]
	v_lshl_add_u64 v[16:17], v[16:17], 0, s[44:45]
	v_pk_mul_f32 v[12:13], v[12:13], v[18:19] op_sel_hi:[1,0]
	v_pk_mul_f32 v[14:15], v[14:15], v[18:19] op_sel_hi:[1,0]
	v_lshl_add_u64 v[16:17], v[16:17], 0, v[156:157]
	v_pk_mul_f32 v[8:9], v[8:9], v[18:19] op_sel_hi:[1,0]
	v_pk_mul_f32 v[10:11], v[10:11], v[18:19] op_sel_hi:[1,0]
	v_pk_mul_f32 v[4:5], v[4:5], v[18:19] op_sel_hi:[1,0]
	v_pk_mul_f32 v[6:7], v[6:7], v[18:19] op_sel_hi:[1,0]
	v_pk_mul_f32 v[0:1], v[0:1], v[18:19] op_sel_hi:[1,0]
	v_pk_mul_f32 v[2:3], v[2:3], v[18:19] op_sel_hi:[1,0]
	s_waitcnt vmcnt(0)
	v_pk_mul_f32 v[12:13], v[20:21], v[12:13]
	v_pk_mul_f32 v[14:15], v[22:23], v[14:15]
	v_cvt_pk_bf16_f32 v12, v12, v13
	v_cvt_pk_bf16_f32 v13, v14, v15
	global_store_dwordx2 v[16:17], v[12:13], off
	global_load_dwordx4 v[12:15], v[40:41], off offset:64
	s_waitcnt vmcnt(0)
	v_pk_mul_f32 v[8:9], v[12:13], v[8:9]
	v_pk_mul_f32 v[10:11], v[14:15], v[10:11]
	v_cvt_pk_bf16_f32 v8, v8, v9
	v_cvt_pk_bf16_f32 v9, v10, v11
	global_store_dwordx2 v[16:17], v[8:9], off offset:32
	global_load_dwordx4 v[8:11], v[40:41], off offset:128
	s_waitcnt vmcnt(0)
	v_pk_mul_f32 v[4:5], v[4:5], v[8:9]
	v_pk_mul_f32 v[6:7], v[6:7], v[10:11]
	v_cvt_pk_bf16_f32 v4, v4, v5
	v_cvt_pk_bf16_f32 v5, v6, v7
	global_store_dwordx2 v[16:17], v[4:5], off offset:64
	global_load_dwordx4 v[4:7], v[40:41], off offset:192
	s_waitcnt vmcnt(0)
	v_pk_mul_f32 v[0:1], v[0:1], v[4:5]
	v_pk_mul_f32 v[2:3], v[2:3], v[6:7]
	v_cvt_pk_bf16_f32 v0, v0, v1
	v_cvt_pk_bf16_f32 v1, v2, v3
	global_store_dwordx2 v[16:17], v[0:1], off offset:96
	s_branch .LBB0_837
